# fp8 K-loops (P2a, P6): post-MFMA barrier issued 4 MFMAs early (hand-off overlap) on top of best
# baseline (speedup 1.0000x reference)
; #define G8_STAGE(bufoff, gbase, NM) do { _Pragma("unroll") for (int _i = 0; _i < 2; ++_i) { \
;     const char* _b = (const char*)(gbase) + (_i ? p2##NM : (size_t)0); asm volatile("" : "+s"(_b));     \
;     __builtin_amdgcn_global_load_lds((const unsigned*)(_b + voff##NM), (LAS unsigned*)(lds + (bufoff) + ldsw + _i * 8192), 16, 0, 0); } } while (0)
; #define G8_WAIT_V(n) asm volatile("s_waitcnt vmcnt(" #n ")" ::: "memory")
; #define G8_WAIT_L(n) asm volatile("s_waitcnt lgkmcnt(" #n ")" ::: "memory")
; #define G8_BAR __builtin_amdgcn_s_barrier()
; #define G8_SCHED __builtin_amdgcn_sched_barrier(0)
;     ...
;     for (int t = 0; t < nt; t += 2) {
;       const bool last = (t == nt - 2);
;       const char* a1 = cA + (size_t)(t + 1) * kstep + hstepA;
;       const char* a2 = last ? nA : cA + (size_t)(t + 2) * kstep; const char* b2 = last ? nB : cB + (size_t)(t + 2) * kstep;
;       const char* a3 = a2 + kstep; const char* b3 = b2 + kstep;
;       asm volatile("" : "+s"(a1), "+s"(a2), "+s"(b2), "+s"(a3), "+s"(b3));
;       G8_LDB(B0, 0, 0); G8_LDB(B1, 0, 1); G8_SCHED; G8_LDA(At, 0, 0); G8_STAGE(G8_SA(1, 1), a1, A);
;       const bool d0a = (BD == 0) || (BD == 1 && t < (nt >> 1)) || (BD == 2 && !(cur.pn & 1));
;       const bool d1a = (BD == 0) || (BD == 1 && t >= (nt >> 1)) || (BD == 2 && !(cur.pn & 1));
;       const bool d0b = (BD == 0) || (BD == 1 && t < (nt >> 1)) || (BD == 2 && (cur.pn & 1));
;       const bool d1b = (BD == 0) || (BD == 1 && t >= (nt >> 1)) || (BD == 2 && (cur.pn & 1));
;       G8_WAIT_V(8); G8_WAIT_L(0); G8_BAR; if (d0a) G8_MMA(0, 0, At, B0); if (d1a) G8_MMA(0, 1, At, B1); G8_BAR; G8_SCHED;
;       G8_LDA(At, 0, 1); G8_STAGE(G8_SB(0, 0), b2, B); G8_STAGE(G8_SB(0, 1), b2 + hstepB, B); G8_STAGE(G8_SA(0, 0), a2, A);
;       G8_WAIT_V(8); G8_WAIT_L(0); G8_BAR; if (d0a) G8_MMA(1, 0, At, B0); if (d1a) G8_MMA(1, 1, At, B1); G8_BAR; G8_SCHED;
.LBB0_413:
	s_add_u32 s44, s34, 0x40080
	s_addc_u32 s45, s35, 0
	s_add_u32 s34, s34, 0x100
	s_addc_u32 s35, s35, 0
	s_cmp_eq_u32 s23, 12
	s_cselect_b32 s40, s24, s34
	s_cselect_b32 s41, s25, s35
	s_cselect_b32 s43, s27, s6
	s_cselect_b32 s42, s26, s5
	s_add_u32 s36, s40, 0x80
	s_addc_u32 s37, s41, 0
	s_add_u32 s38, s42, 0x80
	s_addc_u32 s39, s43, 0
	ds_read_b128 v[144:147], v139
	ds_read_b128 v[148:151], v139 offset:1024
	ds_read_b128 v[152:155], v139 offset:2048
	ds_read_b128 v[156:159], v139 offset:3072
	ds_read_b128 v[160:163], v140
	ds_read_b128 v[164:167], v140 offset:1024
	ds_read_b128 v[168:171], v140 offset:2048
	ds_read_b128 v[172:175], v140 offset:3072
	s_add_i32 m0, s3, 0xc000
	s_mov_b64 s[60:61], s[44:45]
	s_add_u32 s44, s44, 0x20000
	ds_read_b128 v[176:179], v141
	ds_read_b128 v[180:183], v141 offset:1024
	ds_read_b128 v[184:187], v141 offset:2048
	ds_read_b128 v[188:191], v141 offset:3072
	ds_read_b128 v[192:195], v141 offset:4096
	ds_read_b128 v[196:199], v141 offset:5120
	ds_read_b128 v[202:205], v141 offset:6144
	ds_read_b128 v[206:209], v141 offset:7168
	s_addc_u32 s45, s45, 0
	v_lshl_add_u64 v[134:135], s[60:61], 0, v[128:129]
	global_load_lds_dwordx4 v[134:135], off
	s_add_i32 m0, s3, 0xe000
	v_lshl_add_u64 v[134:135], s[44:45], 0, v[128:129]
	global_load_lds_dwordx4 v[134:135], off
	s_waitcnt vmcnt(8)
	s_waitcnt lgkmcnt(0)
	s_barrier
	s_setprio 1
	s_waitcnt lgkmcnt(0)
	v_mfma_f32_16x16x128_f8f6f4 v[124:127], v[144:151], v[176:183], v[124:127]
	v_mfma_f32_16x16x128_f8f6f4 v[120:123], v[152:159], v[176:183], v[120:123]
	v_mfma_f32_16x16x128_f8f6f4 v[108:111], v[144:151], v[184:191], v[108:111]
	v_mfma_f32_16x16x128_f8f6f4 v[104:107], v[152:159], v[184:191], v[104:107]
	v_mfma_f32_16x16x128_f8f6f4 v[134:137], v[144:151], v[192:199], v[92:95]
	v_mfma_f32_16x16x128_f8f6f4 v[210:213], v[152:159], v[192:199], v[88:91]
	v_mfma_f32_16x16x128_f8f6f4 v[214:217], v[144:151], v[202:209], v[76:79]
	v_mfma_f32_16x16x128_f8f6f4 v[218:221], v[152:159], v[202:209], v[72:75]
	s_setprio 0
	s_setprio 1
	v_mfma_f32_16x16x128_f8f6f4 v[116:119], v[160:167], v[176:183], v[116:119]
	v_mfma_f32_16x16x128_f8f6f4 v[112:115], v[168:175], v[176:183], v[112:115]
	v_mfma_f32_16x16x128_f8f6f4 v[100:103], v[160:167], v[184:191], v[100:103]
	v_mfma_f32_16x16x128_f8f6f4 v[96:99], v[168:175], v[184:191], v[96:99]
	s_barrier
	v_mfma_f32_16x16x128_f8f6f4 v[176:179], v[160:167], v[192:199], v[84:87]
	v_mfma_f32_16x16x128_f8f6f4 v[180:183], v[168:175], v[192:199], v[80:83]
	v_mfma_f32_16x16x128_f8f6f4 v[184:187], v[160:167], v[202:209], v[68:71]
	v_mfma_f32_16x16x128_f8f6f4 v[188:191], v[168:175], v[202:209], v[64:67]
	s_setprio 0
	s_mov_b64 s[44:45], s[42:43]
	s_nop 3
	ds_read_b128 v[64:67], v141 offset:16384
	ds_read_b128 v[68:71], v141 offset:17408
	ds_read_b128 v[72:75], v141 offset:18432
	ds_read_b128 v[76:79], v141 offset:19456
	ds_read_b128 v[80:83], v141 offset:20480
	ds_read_b128 v[84:87], v141 offset:21504
	ds_read_b128 v[88:91], v141 offset:22528
	ds_read_b128 v[92:95], v141 offset:23552
	s_add_i32 s60, s50, s0
	v_lshl_add_u64 v[192:193], s[44:45], 0, v[130:131]
	s_add_u32 s44, s42, 0x20000
	s_mov_b32 m0, s60
	s_addc_u32 s45, s43, 0
	global_load_lds_dwordx4 v[192:193], off
	s_add_i32 m0, s60, 0x2000
	v_lshl_add_u64 v[192:193], s[44:45], 0, v[130:131]
	s_add_u32 s44, s42, 0x40000
	s_addc_u32 s45, s43, 0
	global_load_lds_dwordx4 v[192:193], off
	s_nop 0
	v_lshl_add_u64 v[192:193], s[44:45], 0, v[130:131]
	s_add_i32 s44, s51, s0
	s_add_u32 s42, s42, 0x60000
	s_mov_b32 m0, s44
	s_addc_u32 s43, s43, 0
	global_load_lds_dwordx4 v[192:193], off
	s_add_i32 m0, s44, 0x2000
	v_lshl_add_u64 v[192:193], s[42:43], 0, v[130:131]
	s_mov_b64 s[42:43], s[40:41]
	global_load_lds_dwordx4 v[192:193], off
	s_mov_b32 m0, s3
	v_lshl_add_u64 v[192:193], s[42:43], 0, v[128:129]
	s_add_u32 s42, s40, 0x20000
	s_addc_u32 s43, s41, 0
	global_load_lds_dwordx4 v[192:193], off
	s_mov_b32 m0, s33
	v_lshl_add_u64 v[192:193], s[42:43], 0, v[128:129]
	global_load_lds_dwordx4 v[192:193], off
	s_waitcnt vmcnt(8)
	s_waitcnt lgkmcnt(0)
	s_barrier
	s_setprio 1
	s_waitcnt lgkmcnt(0)
	v_mfma_f32_16x16x128_f8f6f4 v[60:63], v[144:151], v[64:71], v[60:63]
	v_mfma_f32_16x16x128_f8f6f4 v[56:59], v[152:159], v[64:71], v[56:59]
	v_mfma_f32_16x16x128_f8f6f4 v[192:195], v[144:151], v[72:79], v[44:47]
	v_mfma_f32_16x16x128_f8f6f4 v[196:199], v[152:159], v[72:79], v[40:43]
	v_mfma_f32_16x16x128_f8f6f4 v[202:205], v[144:151], v[80:87], v[28:31]
	v_mfma_f32_16x16x128_f8f6f4 v[206:209], v[152:159], v[80:87], v[24:27]
	v_mfma_f32_16x16x128_f8f6f4 v[222:225], v[144:151], v[88:95], v[12:15]
	v_mfma_f32_16x16x128_f8f6f4 v[226:229], v[152:159], v[88:95], v[8:11]
	s_setprio 0
	s_setprio 1
	v_mfma_f32_16x16x128_f8f6f4 v[52:55], v[160:167], v[64:71], v[52:55]
	v_mfma_f32_16x16x128_f8f6f4 v[48:51], v[168:175], v[64:71], v[48:51]
	v_mfma_f32_16x16x128_f8f6f4 v[230:233], v[160:167], v[72:79], v[36:39]
	v_mfma_f32_16x16x128_f8f6f4 v[234:237], v[168:175], v[72:79], v[32:35]
	s_barrier
; #define G8_STAGE(bufoff, gbase, NM) do { _Pragma("unroll") for (int _i = 0; _i < 2; ++_i) { \
;     const char* _b = (const char*)(gbase) + (_i ? p2##NM : (size_t)0); asm volatile("" : "+s"(_b));     \
;     __builtin_amdgcn_global_load_lds((const unsigned*)(_b + voff##NM), (LAS unsigned*)(lds + (bufoff) + ldsw + _i * 8192), 16, 0, 0); } } while (0)
; #define G8_WAIT_V(n) asm volatile("s_waitcnt vmcnt(" #n ")" ::: "memory")
; #define G8_WAIT_L(n) asm volatile("s_waitcnt lgkmcnt(" #n ")" ::: "memory")
; #define G8_BAR __builtin_amdgcn_s_barrier()
; #define G8_SCHED __builtin_amdgcn_sched_barrier(0)
;     ...
;       G8_LDA(At, 0, 1); G8_STAGE(G8_SB(0, 0), b2, B); G8_STAGE(G8_SB(0, 1), b2 + hstepB, B); G8_STAGE(G8_SA(0, 0), a2, A);
;       G8_WAIT_V(8); G8_WAIT_L(0); G8_BAR; if (d0a) G8_MMA(1, 0, At, B0); if (d1a) G8_MMA(1, 1, At, B1); G8_BAR; G8_SCHED;
;       G8_LDB(B0, 1, 0); G8_LDB(B1, 1, 1); G8_SCHED; G8_LDA(At, 1, 0); G8_STAGE(G8_SA(0, 1), a2 + hstepA, A);
;       G8_WAIT_V(8); G8_WAIT_L(0); G8_BAR; if (d0b) G8_MMA(0, 0, At, B0); if (d1b) G8_MMA(0, 1, At, B1); G8_BAR; G8_SCHED;
;       G8_LDA(At, 1, 1); G8_STAGE(G8_SB(1, 0), b3, B); G8_STAGE(G8_SB(1, 1), b3 + hstepB, B); G8_STAGE(G8_SA(1, 0), a3, A);
;       G8_WAIT_V(8); G8_WAIT_L(0); G8_BAR; if (d0b) G8_MMA(1, 0, At, B0); if (d1b) G8_MMA(1, 1, At, B1); G8_BAR; G8_SCHED;
	v_mfma_f32_16x16x128_f8f6f4 v[238:241], v[160:167], v[80:87], v[20:23]
	v_mfma_f32_16x16x128_f8f6f4 v[242:245], v[168:175], v[80:87], v[16:19]
	v_mfma_f32_16x16x128_f8f6f4 v[246:249], v[160:167], v[88:95], v[4:7]
	v_mfma_f32_16x16x128_f8f6f4 v[250:253], v[168:175], v[88:95], v[0:3]
	s_setprio 0
	s_add_i32 s44, 0, 0x18000
	v_add_u32_e32 v8, s44, v138
	s_add_i32 s45, 0, 0x1c000
	s_nop 1
	ds_read_b128 v[0:3], v8
	ds_read_b128 v[4:7], v8 offset:1024
	ds_read_b128 v[16:19], v8 offset:2048
	ds_read_b128 v[20:23], v8 offset:3072
	v_add_u32_e32 v8, 0x1000, v8
	ds_read_b128 v[144:147], v8
	ds_read_b128 v[148:151], v8 offset:1024
	ds_read_b128 v[152:155], v8 offset:2048
	ds_read_b128 v[156:159], v8 offset:3072
	s_add_u32 s42, s40, 0x40000
	s_addc_u32 s43, s41, 0
	s_add_u32 s40, s40, 0x60000
	s_mov_b32 m0, s46
	ds_read_b128 v[8:11], v141 offset:32768
	ds_read_b128 v[12:15], v141 offset:33792
	ds_read_b128 v[24:27], v141 offset:34816
	ds_read_b128 v[28:31], v141 offset:35840
	ds_read_b128 v[32:35], v141 offset:36864
	ds_read_b128 v[36:39], v141 offset:37888
	ds_read_b128 v[40:43], v141 offset:38912
	ds_read_b128 v[44:47], v141 offset:39936
	s_addc_u32 s41, s41, 0
	v_lshl_add_u64 v[64:65], s[42:43], 0, v[128:129]
	global_load_lds_dwordx4 v[64:65], off
	s_mov_b32 m0, s47
	v_lshl_add_u64 v[64:65], s[40:41], 0, v[128:129]
	global_load_lds_dwordx4 v[64:65], off
	s_waitcnt vmcnt(8)
	s_waitcnt lgkmcnt(0)
	s_barrier
	s_setprio 1
	s_waitcnt lgkmcnt(0)
	v_mfma_f32_16x16x128_f8f6f4 v[124:127], v[0:7], v[8:15], v[124:127]
	v_mfma_f32_16x16x128_f8f6f4 v[120:123], v[16:23], v[8:15], v[120:123]
	v_mfma_f32_16x16x128_f8f6f4 v[108:111], v[0:7], v[24:31], v[108:111]
	v_mfma_f32_16x16x128_f8f6f4 v[104:107], v[16:23], v[24:31], v[104:107]
	v_mfma_f32_16x16x128_f8f6f4 v[92:95], v[0:7], v[32:39], v[134:137]
	v_mfma_f32_16x16x128_f8f6f4 v[88:91], v[16:23], v[32:39], v[210:213]
	v_mfma_f32_16x16x128_f8f6f4 v[76:79], v[0:7], v[40:47], v[214:217]
	v_mfma_f32_16x16x128_f8f6f4 v[72:75], v[16:23], v[40:47], v[218:221]
	s_setprio 0
	s_setprio 1
	v_mfma_f32_16x16x128_f8f6f4 v[116:119], v[144:151], v[8:15], v[116:119]
	v_mfma_f32_16x16x128_f8f6f4 v[112:115], v[152:159], v[8:15], v[112:115]
	v_mfma_f32_16x16x128_f8f6f4 v[100:103], v[144:151], v[24:31], v[100:103]
	v_mfma_f32_16x16x128_f8f6f4 v[96:99], v[152:159], v[24:31], v[96:99]
	s_barrier
	v_mfma_f32_16x16x128_f8f6f4 v[84:87], v[144:151], v[32:39], v[176:179]
	v_mfma_f32_16x16x128_f8f6f4 v[80:83], v[152:159], v[32:39], v[180:183]
	v_mfma_f32_16x16x128_f8f6f4 v[68:71], v[144:151], v[40:47], v[184:187]
	v_mfma_f32_16x16x128_f8f6f4 v[64:67], v[152:159], v[40:47], v[188:191]
	s_setprio 0
	s_mov_b64 s[40:41], s[38:39]
	ds_read_b128 v[32:35], v141 offset:49152
	ds_read_b128 v[36:39], v141 offset:50176
	ds_read_b128 v[160:163], v141 offset:51200
	ds_read_b128 v[164:167], v141 offset:52224
	ds_read_b128 v[168:171], v141 offset:53248
	ds_read_b128 v[172:175], v141 offset:54272
	ds_read_b128 v[176:179], v141 offset:55296
	ds_read_b128 v[180:183], v141 offset:56320
	s_add_i32 s42, s44, s0
	v_lshl_add_u64 v[8:9], s[40:41], 0, v[130:131]
	s_add_u32 s40, s38, 0x20000
	s_mov_b32 m0, s42
	s_addc_u32 s41, s39, 0
	global_load_lds_dwordx4 v[8:9], off
	s_add_i32 m0, s42, 0x2000
	v_lshl_add_u64 v[8:9], s[40:41], 0, v[130:131]
	s_add_u32 s40, s38, 0x40000
	s_addc_u32 s41, s39, 0
	global_load_lds_dwordx4 v[8:9], off
	s_nop 0
	v_lshl_add_u64 v[8:9], s[40:41], 0, v[130:131]
	s_add_i32 s40, s45, s0
	s_add_u32 s38, s38, 0x60000
	s_mov_b32 m0, s40
	s_addc_u32 s39, s39, 0
	global_load_lds_dwordx4 v[8:9], off
	s_add_i32 m0, s40, 0x2000
	v_lshl_add_u64 v[8:9], s[38:39], 0, v[130:131]
	s_mov_b64 s[38:39], s[36:37]
	s_add_u32 s36, s36, 0x20000
	global_load_lds_dwordx4 v[8:9], off
	s_mov_b32 m0, s48
	v_lshl_add_u64 v[8:9], s[38:39], 0, v[128:129]
	s_addc_u32 s37, s37, 0
	global_load_lds_dwordx4 v[8:9], off
	s_mov_b32 m0, s49
	v_lshl_add_u64 v[8:9], s[36:37], 0, v[128:129]
	global_load_lds_dwordx4 v[8:9], off
	s_waitcnt vmcnt(8)
	s_waitcnt lgkmcnt(0)
	s_barrier
	s_setprio 1
	s_waitcnt lgkmcnt(0)
	v_mfma_f32_16x16x128_f8f6f4 v[60:63], v[0:7], v[32:39], v[60:63]
	v_mfma_f32_16x16x128_f8f6f4 v[56:59], v[16:23], v[32:39], v[56:59]
	v_mfma_f32_16x16x128_f8f6f4 v[44:47], v[0:7], v[160:167], v[192:195]
	v_mfma_f32_16x16x128_f8f6f4 v[40:43], v[16:23], v[160:167], v[196:199]
	v_mfma_f32_16x16x128_f8f6f4 v[28:31], v[0:7], v[168:175], v[202:205]
	v_mfma_f32_16x16x128_f8f6f4 v[24:27], v[16:23], v[168:175], v[206:209]
	v_mfma_f32_16x16x128_f8f6f4 v[12:15], v[0:7], v[176:183], v[222:225]
	v_mfma_f32_16x16x128_f8f6f4 v[8:11], v[16:23], v[176:183], v[226:229]
	s_setprio 0
	s_setprio 1
	v_mfma_f32_16x16x128_f8f6f4 v[52:55], v[144:151], v[32:39], v[52:55]
	v_mfma_f32_16x16x128_f8f6f4 v[48:51], v[152:159], v[32:39], v[48:51]
	v_mfma_f32_16x16x128_f8f6f4 v[36:39], v[144:151], v[160:167], v[230:233]
	v_mfma_f32_16x16x128_f8f6f4 v[32:35], v[152:159], v[160:167], v[234:237]
	s_barrier
	v_mfma_f32_16x16x128_f8f6f4 v[20:23], v[144:151], v[168:175], v[238:241]
	v_mfma_f32_16x16x128_f8f6f4 v[16:19], v[152:159], v[168:175], v[242:245]
	v_mfma_f32_16x16x128_f8f6f4 v[4:7], v[144:151], v[176:183], v[246:249]
	v_mfma_f32_16x16x128_f8f6f4 v[0:3], v[152:159], v[176:183], v[250:253]
	s_setprio 0
	s_add_i32 s23, s23, 2
	s_add_u32 s5, s5, 0x100
	s_addc_u32 s6, s6, 0
	s_cmp_gt_u32 s23, 13
	s_cbranch_scc0 .LBB0_413
	s_and_b64 vcc, exec, s[10:11]
	s_cbranch_vccz .LBB0_416
	s_barrier

; #define G8_STAGE(bufoff, gbase, NM) do { _Pragma("unroll") for (int _i = 0; _i < 2; ++_i) { \
;     const char* _b = (const char*)(gbase) + (_i ? p2##NM : (size_t)0); asm volatile("" : "+s"(_b));     \
;     __builtin_amdgcn_global_load_lds((const unsigned*)(_b + voff##NM), (LAS unsigned*)(lds + (bufoff) + ldsw + _i * 8192), 16, 0, 0); } } while (0)
; #define G8_WAIT_V(n) asm volatile("s_waitcnt vmcnt(" #n ")" ::: "memory")
; #define G8_WAIT_L(n) asm volatile("s_waitcnt lgkmcnt(" #n ")" ::: "memory")
; #define G8_BAR __builtin_amdgcn_s_barrier()
; #define G8_SCHED __builtin_amdgcn_sched_barrier(0)
;     ...
;     for (int t = 0; t < nt; t += 2) {
;       const bool last = (t == nt - 2);
;       const char* a1 = cA + (size_t)(t + 1) * kstep + hstepA;
;       const char* a2 = last ? nA : cA + (size_t)(t + 2) * kstep; const char* b2 = last ? nB : cB + (size_t)(t + 2) * kstep;
;       const char* a3 = a2 + kstep; const char* b3 = b2 + kstep;
;       asm volatile("" : "+s"(a1), "+s"(a2), "+s"(b2), "+s"(a3), "+s"(b3));
;       G8_LDB(B0, 0, 0); G8_LDB(B1, 0, 1); G8_SCHED; G8_LDA(At, 0, 0); G8_STAGE(G8_SA(1, 1), a1, A);
;       const bool d0a = (BD == 0) || (BD == 1 && t < (nt >> 1)) || (BD == 2 && !(cur.pn & 1));
;       const bool d1a = (BD == 0) || (BD == 1 && t >= (nt >> 1)) || (BD == 2 && !(cur.pn & 1));
;       const bool d0b = (BD == 0) || (BD == 1 && t < (nt >> 1)) || (BD == 2 && (cur.pn & 1));
;       const bool d1b = (BD == 0) || (BD == 1 && t >= (nt >> 1)) || (BD == 2 && (cur.pn & 1));
;       G8_WAIT_V(8); G8_WAIT_L(0); G8_BAR; if (d0a) G8_MMA(0, 0, At, B0); if (d1a) G8_MMA(0, 1, At, B1); G8_BAR; G8_SCHED;
;       G8_LDA(At, 0, 1); G8_STAGE(G8_SB(0, 0), b2, B); G8_STAGE(G8_SB(0, 1), b2 + hstepB, B); G8_STAGE(G8_SA(0, 0), a2, A);
;       G8_WAIT_V(8); G8_WAIT_L(0); G8_BAR; if (d0a) G8_MMA(1, 0, At, B0); if (d1a) G8_MMA(1, 1, At, B1); G8_BAR; G8_SCHED;
.LBB0_1078:
	s_add_u32 s36, s24, 0x80080
	s_addc_u32 s37, s25, 0
	s_add_u32 s24, s24, 0x100
	s_addc_u32 s25, s25, 0
	s_cmp_eq_u32 s47, 28
	s_cselect_b32 s30, s18, s24
	s_cselect_b32 s31, s19, s25
	s_cselect_b32 s35, s21, s23
	s_cselect_b32 s34, s20, s17
	s_add_u32 s26, s30, 0x80
	s_addc_u32 s27, s31, 0
	s_add_u32 s28, s34, 0x80
	s_addc_u32 s29, s35, 0
	ds_read_b128 v[140:143], v137
	ds_read_b128 v[144:147], v137 offset:1024
	ds_read_b128 v[148:151], v137 offset:2048
	ds_read_b128 v[152:155], v137 offset:3072
	ds_read_b128 v[156:159], v138
	ds_read_b128 v[160:163], v138 offset:1024
	ds_read_b128 v[164:167], v138 offset:2048
	ds_read_b128 v[168:171], v138 offset:3072
	s_add_i32 m0, s3, 0xc000
	s_mov_b64 s[48:49], s[36:37]
	s_add_u32 s36, s36, 0x40000
	ds_read_b128 v[172:175], v139
	ds_read_b128 v[176:179], v139 offset:1024
	ds_read_b128 v[180:183], v139 offset:2048
	ds_read_b128 v[184:187], v139 offset:3072
	ds_read_b128 v[188:191], v139 offset:4096
	ds_read_b128 v[192:195], v139 offset:5120
	ds_read_b128 v[202:205], v139 offset:6144
	ds_read_b128 v[206:209], v139 offset:7168
	s_addc_u32 s37, s37, 0
	v_lshl_add_u64 v[132:133], s[48:49], 0, v[128:129]
	global_load_lds_dwordx4 v[132:133], off
	s_add_i32 m0, s3, 0xe000
	v_lshl_add_u64 v[132:133], s[36:37], 0, v[128:129]
	global_load_lds_dwordx4 v[132:133], off
	s_waitcnt vmcnt(8)
	s_waitcnt lgkmcnt(0)
	s_barrier
	s_setprio 1
	s_waitcnt lgkmcnt(0)
	v_mfma_f32_16x16x128_f8f6f4 v[124:127], v[140:147], v[172:179], v[124:127]
	v_mfma_f32_16x16x128_f8f6f4 v[120:123], v[148:155], v[172:179], v[120:123]
	v_mfma_f32_16x16x128_f8f6f4 v[108:111], v[140:147], v[180:187], v[108:111]
	v_mfma_f32_16x16x128_f8f6f4 v[104:107], v[148:155], v[180:187], v[104:107]
	v_mfma_f32_16x16x128_f8f6f4 v[132:135], v[140:147], v[188:195], v[92:95]
	v_mfma_f32_16x16x128_f8f6f4 v[196:199], v[148:155], v[188:195], v[88:91]
	v_mfma_f32_16x16x128_f8f6f4 v[210:213], v[140:147], v[202:209], v[76:79]
	v_mfma_f32_16x16x128_f8f6f4 v[214:217], v[148:155], v[202:209], v[72:75]
	s_setprio 0
	s_setprio 1
	v_mfma_f32_16x16x128_f8f6f4 v[116:119], v[156:163], v[172:179], v[116:119]
	v_mfma_f32_16x16x128_f8f6f4 v[112:115], v[164:171], v[172:179], v[112:115]
	v_mfma_f32_16x16x128_f8f6f4 v[100:103], v[156:163], v[180:187], v[100:103]
	v_mfma_f32_16x16x128_f8f6f4 v[96:99], v[164:171], v[180:187], v[96:99]
	s_barrier
	v_mfma_f32_16x16x128_f8f6f4 v[172:175], v[156:163], v[188:195], v[84:87]
	v_mfma_f32_16x16x128_f8f6f4 v[176:179], v[164:171], v[188:195], v[80:83]
	v_mfma_f32_16x16x128_f8f6f4 v[180:183], v[156:163], v[202:209], v[68:71]
	v_mfma_f32_16x16x128_f8f6f4 v[184:187], v[164:171], v[202:209], v[64:67]
	s_setprio 0
	s_mov_b64 s[36:37], s[34:35]
	s_nop 3
	ds_read_b128 v[64:67], v139 offset:16384
	ds_read_b128 v[68:71], v139 offset:17408
	ds_read_b128 v[72:75], v139 offset:18432
	ds_read_b128 v[76:79], v139 offset:19456
	ds_read_b128 v[80:83], v139 offset:20480
	ds_read_b128 v[84:87], v139 offset:21504
	ds_read_b128 v[88:91], v139 offset:22528
	ds_read_b128 v[92:95], v139 offset:23552
	s_add_i32 s48, s42, s2
	v_lshl_add_u64 v[188:189], s[36:37], 0, v[130:131]
	s_add_u32 s36, s34, 0x40000
	s_mov_b32 m0, s48
	s_addc_u32 s37, s35, 0
	global_load_lds_dwordx4 v[188:189], off
	s_add_i32 m0, s48, 0x2000
	v_lshl_add_u64 v[188:189], s[36:37], 0, v[130:131]
	s_add_u32 s36, s34, 0x80000
	s_addc_u32 s37, s35, 0
	global_load_lds_dwordx4 v[188:189], off
	s_nop 0
	v_lshl_add_u64 v[188:189], s[36:37], 0, v[130:131]
	s_add_i32 s36, s43, s2
	s_add_u32 s34, s34, 0xc0000
	s_mov_b32 m0, s36
	s_addc_u32 s35, s35, 0
	global_load_lds_dwordx4 v[188:189], off
	s_add_i32 m0, s36, 0x2000
	v_lshl_add_u64 v[188:189], s[34:35], 0, v[130:131]
	s_mov_b64 s[34:35], s[30:31]
	global_load_lds_dwordx4 v[188:189], off
	s_mov_b32 m0, s3
	v_lshl_add_u64 v[188:189], s[34:35], 0, v[128:129]
	s_add_u32 s34, s30, 0x40000
	s_addc_u32 s35, s31, 0
	global_load_lds_dwordx4 v[188:189], off
	s_mov_b32 m0, s13
	v_lshl_add_u64 v[188:189], s[34:35], 0, v[128:129]
	global_load_lds_dwordx4 v[188:189], off
	s_waitcnt vmcnt(8)
	s_waitcnt lgkmcnt(0)
	s_barrier
	s_setprio 1
	s_waitcnt lgkmcnt(0)
	v_mfma_f32_16x16x128_f8f6f4 v[60:63], v[140:147], v[64:71], v[60:63]
	v_mfma_f32_16x16x128_f8f6f4 v[56:59], v[148:155], v[64:71], v[56:59]
	v_mfma_f32_16x16x128_f8f6f4 v[188:191], v[140:147], v[72:79], v[44:47]
	v_mfma_f32_16x16x128_f8f6f4 v[192:195], v[148:155], v[72:79], v[40:43]
	v_mfma_f32_16x16x128_f8f6f4 v[202:205], v[140:147], v[80:87], v[28:31]
	v_mfma_f32_16x16x128_f8f6f4 v[206:209], v[148:155], v[80:87], v[24:27]
	v_mfma_f32_16x16x128_f8f6f4 v[218:221], v[140:147], v[88:95], v[12:15]
	v_mfma_f32_16x16x128_f8f6f4 v[222:225], v[148:155], v[88:95], v[8:11]
	s_setprio 0
	s_setprio 1
	v_mfma_f32_16x16x128_f8f6f4 v[52:55], v[156:163], v[64:71], v[52:55]
	v_mfma_f32_16x16x128_f8f6f4 v[48:51], v[164:171], v[64:71], v[48:51]
	v_mfma_f32_16x16x128_f8f6f4 v[226:229], v[156:163], v[72:79], v[36:39]
	v_mfma_f32_16x16x128_f8f6f4 v[230:233], v[164:171], v[72:79], v[32:35]
	s_barrier
; #define G8_STAGE(bufoff, gbase, NM) do { _Pragma("unroll") for (int _i = 0; _i < 2; ++_i) { \
;     const char* _b = (const char*)(gbase) + (_i ? p2##NM : (size_t)0); asm volatile("" : "+s"(_b));     \
;     __builtin_amdgcn_global_load_lds((const unsigned*)(_b + voff##NM), (LAS unsigned*)(lds + (bufoff) + ldsw + _i * 8192), 16, 0, 0); } } while (0)
; #define G8_WAIT_V(n) asm volatile("s_waitcnt vmcnt(" #n ")" ::: "memory")
; #define G8_WAIT_L(n) asm volatile("s_waitcnt lgkmcnt(" #n ")" ::: "memory")
; #define G8_BAR __builtin_amdgcn_s_barrier()
; #define G8_SCHED __builtin_amdgcn_sched_barrier(0)
;     ...
;       G8_LDA(At, 0, 1); G8_STAGE(G8_SB(0, 0), b2, B); G8_STAGE(G8_SB(0, 1), b2 + hstepB, B); G8_STAGE(G8_SA(0, 0), a2, A);
;       G8_WAIT_V(8); G8_WAIT_L(0); G8_BAR; if (d0a) G8_MMA(1, 0, At, B0); if (d1a) G8_MMA(1, 1, At, B1); G8_BAR; G8_SCHED;
;       G8_LDB(B0, 1, 0); G8_LDB(B1, 1, 1); G8_SCHED; G8_LDA(At, 1, 0); G8_STAGE(G8_SA(0, 1), a2 + hstepA, A);
;       G8_WAIT_V(8); G8_WAIT_L(0); G8_BAR; if (d0b) G8_MMA(0, 0, At, B0); if (d1b) G8_MMA(0, 1, At, B1); G8_BAR; G8_SCHED;
;       G8_LDA(At, 1, 1); G8_STAGE(G8_SB(1, 0), b3, B); G8_STAGE(G8_SB(1, 1), b3 + hstepB, B); G8_STAGE(G8_SA(1, 0), a3, A);
;       G8_WAIT_V(8); G8_WAIT_L(0); G8_BAR; if (d0b) G8_MMA(1, 0, At, B0); if (d1b) G8_MMA(1, 1, At, B1); G8_BAR; G8_SCHED;
	v_mfma_f32_16x16x128_f8f6f4 v[234:237], v[156:163], v[80:87], v[20:23]
	v_mfma_f32_16x16x128_f8f6f4 v[238:241], v[164:171], v[80:87], v[16:19]
	v_mfma_f32_16x16x128_f8f6f4 v[242:245], v[156:163], v[88:95], v[4:7]
	v_mfma_f32_16x16x128_f8f6f4 v[246:249], v[164:171], v[88:95], v[0:3]
	s_setprio 0
	s_add_i32 s36, 0, 0x18000
	v_add_u32_e32 v8, s36, v136
	s_add_i32 s37, 0, 0x1c000
	s_nop 1
	ds_read_b128 v[0:3], v8
	ds_read_b128 v[4:7], v8 offset:1024
	ds_read_b128 v[16:19], v8 offset:2048
	ds_read_b128 v[20:23], v8 offset:3072
	v_add_u32_e32 v8, 0x1000, v8
	ds_read_b128 v[140:143], v8
	ds_read_b128 v[144:147], v8 offset:1024
	ds_read_b128 v[148:151], v8 offset:2048
	ds_read_b128 v[152:155], v8 offset:3072
	s_add_u32 s34, s30, 0x80000
	s_addc_u32 s35, s31, 0
	s_add_u32 s30, s30, 0xc0000
	s_mov_b32 m0, s33
	ds_read_b128 v[8:11], v139 offset:32768
	ds_read_b128 v[12:15], v139 offset:33792
	ds_read_b128 v[24:27], v139 offset:34816
	ds_read_b128 v[28:31], v139 offset:35840
	ds_read_b128 v[32:35], v139 offset:36864
	ds_read_b128 v[36:39], v139 offset:37888
	ds_read_b128 v[40:43], v139 offset:38912
	ds_read_b128 v[44:47], v139 offset:39936
	s_addc_u32 s31, s31, 0
	v_lshl_add_u64 v[64:65], s[34:35], 0, v[128:129]
	global_load_lds_dwordx4 v[64:65], off
	s_mov_b32 m0, s38
	v_lshl_add_u64 v[64:65], s[30:31], 0, v[128:129]
	global_load_lds_dwordx4 v[64:65], off
	s_waitcnt vmcnt(8)
	s_waitcnt lgkmcnt(0)
	s_barrier
	s_setprio 1
	s_waitcnt lgkmcnt(0)
	v_mfma_f32_16x16x128_f8f6f4 v[124:127], v[0:7], v[8:15], v[124:127]
	v_mfma_f32_16x16x128_f8f6f4 v[120:123], v[16:23], v[8:15], v[120:123]
	v_mfma_f32_16x16x128_f8f6f4 v[108:111], v[0:7], v[24:31], v[108:111]
	v_mfma_f32_16x16x128_f8f6f4 v[104:107], v[16:23], v[24:31], v[104:107]
	v_mfma_f32_16x16x128_f8f6f4 v[92:95], v[0:7], v[32:39], v[132:135]
	v_mfma_f32_16x16x128_f8f6f4 v[88:91], v[16:23], v[32:39], v[196:199]
	v_mfma_f32_16x16x128_f8f6f4 v[76:79], v[0:7], v[40:47], v[210:213]
	v_mfma_f32_16x16x128_f8f6f4 v[72:75], v[16:23], v[40:47], v[214:217]
	s_setprio 0
	s_setprio 1
	v_mfma_f32_16x16x128_f8f6f4 v[116:119], v[140:147], v[8:15], v[116:119]
	v_mfma_f32_16x16x128_f8f6f4 v[112:115], v[148:155], v[8:15], v[112:115]
	v_mfma_f32_16x16x128_f8f6f4 v[100:103], v[140:147], v[24:31], v[100:103]
	v_mfma_f32_16x16x128_f8f6f4 v[96:99], v[148:155], v[24:31], v[96:99]
	s_barrier
	v_mfma_f32_16x16x128_f8f6f4 v[84:87], v[140:147], v[32:39], v[172:175]
	v_mfma_f32_16x16x128_f8f6f4 v[80:83], v[148:155], v[32:39], v[176:179]
	v_mfma_f32_16x16x128_f8f6f4 v[68:71], v[140:147], v[40:47], v[180:183]
	v_mfma_f32_16x16x128_f8f6f4 v[64:67], v[148:155], v[40:47], v[184:187]
	s_setprio 0
	s_mov_b64 s[30:31], s[28:29]
	ds_read_b128 v[32:35], v139 offset:49152
	ds_read_b128 v[36:39], v139 offset:50176
	ds_read_b128 v[156:159], v139 offset:51200
	ds_read_b128 v[160:163], v139 offset:52224
	ds_read_b128 v[164:167], v139 offset:53248
	ds_read_b128 v[168:171], v139 offset:54272
	ds_read_b128 v[172:175], v139 offset:55296
	ds_read_b128 v[176:179], v139 offset:56320
	s_add_i32 s34, s36, s2
	v_lshl_add_u64 v[8:9], s[30:31], 0, v[130:131]
	s_add_u32 s30, s28, 0x40000
	s_mov_b32 m0, s34
	s_addc_u32 s31, s29, 0
	global_load_lds_dwordx4 v[8:9], off
	s_add_i32 m0, s34, 0x2000
	v_lshl_add_u64 v[8:9], s[30:31], 0, v[130:131]
	s_add_u32 s30, s28, 0x80000
	s_addc_u32 s31, s29, 0
	global_load_lds_dwordx4 v[8:9], off
	s_nop 0
	v_lshl_add_u64 v[8:9], s[30:31], 0, v[130:131]
	s_add_i32 s30, s37, s2
	s_add_u32 s28, s28, 0xc0000
	s_mov_b32 m0, s30
	s_addc_u32 s29, s29, 0
	global_load_lds_dwordx4 v[8:9], off
	s_add_i32 m0, s30, 0x2000
	v_lshl_add_u64 v[8:9], s[28:29], 0, v[130:131]
	s_mov_b64 s[28:29], s[26:27]
	s_add_u32 s26, s26, 0x40000
	global_load_lds_dwordx4 v[8:9], off
	s_mov_b32 m0, s40
	v_lshl_add_u64 v[8:9], s[28:29], 0, v[128:129]
	s_addc_u32 s27, s27, 0
	global_load_lds_dwordx4 v[8:9], off
	s_mov_b32 m0, s41
	v_lshl_add_u64 v[8:9], s[26:27], 0, v[128:129]
	global_load_lds_dwordx4 v[8:9], off
	s_waitcnt vmcnt(8)
	s_waitcnt lgkmcnt(0)
	s_barrier
	s_setprio 1
	s_waitcnt lgkmcnt(0)
	v_mfma_f32_16x16x128_f8f6f4 v[60:63], v[0:7], v[32:39], v[60:63]
	v_mfma_f32_16x16x128_f8f6f4 v[56:59], v[16:23], v[32:39], v[56:59]
	v_mfma_f32_16x16x128_f8f6f4 v[44:47], v[0:7], v[156:163], v[188:191]
	v_mfma_f32_16x16x128_f8f6f4 v[40:43], v[16:23], v[156:163], v[192:195]
	v_mfma_f32_16x16x128_f8f6f4 v[28:31], v[0:7], v[164:171], v[202:205]
	v_mfma_f32_16x16x128_f8f6f4 v[24:27], v[16:23], v[164:171], v[206:209]
	v_mfma_f32_16x16x128_f8f6f4 v[12:15], v[0:7], v[172:179], v[218:221]
	v_mfma_f32_16x16x128_f8f6f4 v[8:11], v[16:23], v[172:179], v[222:225]
	s_setprio 0
	s_setprio 1
	v_mfma_f32_16x16x128_f8f6f4 v[52:55], v[140:147], v[32:39], v[52:55]
	v_mfma_f32_16x16x128_f8f6f4 v[48:51], v[148:155], v[32:39], v[48:51]
	v_mfma_f32_16x16x128_f8f6f4 v[36:39], v[140:147], v[156:163], v[226:229]
	v_mfma_f32_16x16x128_f8f6f4 v[32:35], v[148:155], v[156:163], v[230:233]
	s_barrier
	v_mfma_f32_16x16x128_f8f6f4 v[20:23], v[140:147], v[164:171], v[234:237]
	v_mfma_f32_16x16x128_f8f6f4 v[16:19], v[148:155], v[164:171], v[238:241]
	v_mfma_f32_16x16x128_f8f6f4 v[4:7], v[140:147], v[172:179], v[242:245]
	v_mfma_f32_16x16x128_f8f6f4 v[0:3], v[148:155], v[172:179], v[246:249]
	s_setprio 0
	s_add_i32 s47, s47, 2
	s_add_u32 s17, s17, 0x100
	s_addc_u32 s23, s23, 0
	s_cmp_gt_u32 s47, 29
	s_cbranch_scc0 .LBB0_1078
	s_and_b64 vcc, exec, s[10:11]
	s_cbranch_vccz .LBB0_1081
	s_barrier
